# conv0-conv1 seam: no L2 writeback or invalidate either (dependency is workgroup-local)
# baseline (speedup 1.0000x reference)
; __device__ __forceinline__ void grid_bar(unsigned* ctr, unsigned target, int wave) {
;     __builtin_amdgcn_s_waitcnt(0x0F70);
;     __syncthreads();
;     if (wave == 0) {
;         int l; asm volatile("v_mbcnt_lo_u32_b32 %0, -1, 0\n\tv_mbcnt_hi_u32_b32 %0, -1, %0" : "=v"(l));
;         if (l == 0) {
;             __builtin_amdgcn_fence(__ATOMIC_RELEASE, "agent");
;             __hip_atomic_fetch_add(ctr, 1u, __ATOMIC_RELAXED, __HIP_MEMORY_SCOPE_AGENT);
;             while (__hip_atomic_load(ctr, __ATOMIC_RELAXED, __HIP_MEMORY_SCOPE_AGENT) < target) __builtin_amdgcn_s_sleep(2);
;             __builtin_amdgcn_fence(__ATOMIC_ACQUIRE, "agent");
;         }
;     }
;     __syncthreads();
; }
.LBB0_700:
	s_andn2_b64 vcc, exec, s[22:23]
	s_cbranch_vccnz .LBB0_198
	s_or_b32 s3, s41, 4
	s_cmp_ge_i32 s3, s73
	s_cbranch_scc1 .LBB0_198
	v_readlane_b32 s0, v254, 4
	v_readlane_b32 s1, v254, 5
	s_andn2_b64 vcc, exec, s[0:1]
	s_waitcnt vmcnt(0) lgkmcnt(0)
	s_barrier
	s_cbranch_vccnz .LBB0_197
	v_mbcnt_lo_u32_b32 v0, -1, 0
	v_mbcnt_hi_u32_b32 v0, -1, v0
	s_nop 0
	v_cmp_eq_u32_e32 vcc, 0, v0
	s_and_saveexec_b64 s[0:1], vcc
	s_cbranch_execz .LBB0_196
	s_mov_b64 s[4:5], exec
	v_mbcnt_lo_u32_b32 v0, s4, 0
	v_mbcnt_hi_u32_b32 v0, s5, v0
	v_cmp_eq_u32_e32 vcc, 0, v0
	s_cmp_eq_u32 s41, 0
	s_cbranch_scc1 .Lseam3_nowb
	buffer_wbl2 sc1
.Lseam3_nowb:
	s_and_saveexec_b64 s[6:7], vcc
	s_cbranch_execz .LBB0_706
	s_bcnt1_i32_b64 s4, s[4:5]
	v_mov_b32_e32 v0, s4
	v_readlane_b32 s4, v253, 61
	v_readlane_b32 s5, v253, 62
	s_nop 4
	global_atomic_add v57, v0, s[4:5]
